# layer-1 projection weight bf16 pre-conversion moved from kernel entry to idle blocks of the layer-0 top-k phase
# speedup vs baseline: 1.0035x; 1.0035x over previous
.Lcc_skip:
	s_mov_b32 s12, s2
	s_movk_i32 s22, 0x2ff
	s_cmp_eq_u32 s3, 0x200
	s_cselect_b32 s22, 0x15f, s22
.Lwc_loop:
	s_cmp_gt_u32 s12, s22
	s_cbranch_scc1 .Lwc_done
	s_lshr_b32 s13, s12, 4
	s_and_b32 s14, s12, 15
	s_mov_b64 s[16:17], s[4:5]
	s_movk_i32 s15, 0x1c00
	s_mov_b32 s18, s13
	s_cmp_lt_u32 s13, 14
	s_cbranch_scc1 .Lwc_sel
	s_mov_b64 s[16:17], s[6:7]
	s_movk_i32 s15, 0x1000
	s_sub_u32 s18, s13, 14
	s_cmp_lt_u32 s13, 22
	s_cbranch_scc1 .Lwc_sel
	s_mov_b64 s[16:17], s[8:9]
	s_movk_i32 s15, 0x2400
	s_sub_u32 s18, s13, 22
	s_cmp_lt_u32 s13, 40
	s_cbranch_scc1 .Lwc_sel
	s_mov_b64 s[16:17], s[10:11]
	s_movk_i32 s15, 0x1000
	s_sub_u32 s18, s13, 40

.LtkA_eq15:
	s_add_i32 s33, s33, s92
	s_cmp_lt_i32 s33, 32
	s_barrier
	s_cbranch_scc1 .LtkA_item
	s_branch .LBB0_1129
.Ldc_conv:
	s_cmpk_gt_u32 s97, 0x1bf
	s_cbranch_scc1 .LBB0_1129
	s_cmp_lg_u32 s92, 0x200
	s_cbranch_scc1 .LBB0_1129
	v_readlane_b32 s0, v253, 4
	v_readlane_b32 s1, v253, 5
	s_nop 1
	s_sub_u32 s0, s0, 0x228
	s_subb_u32 s1, s1, 0
	s_load_dwordx2 s[8:9], s[0:1], 0xb8
	s_load_dwordx2 s[10:11], s[0:1], 0xd8
	s_add_u32 s12, s97, 0x140
	v_lshrrev_b32_e32 v2, 6, v250
	v_and_b32_e32 v3, 63, v250
	v_lshlrev_b32_e32 v2, 12, v2
	v_lshl_or_b32 v2, v3, 4, v2
	v_and_b32_e32 v3, 31, v250
	v_lshrrev_b32_e32 v4, 5, v250
	v_lshlrev_b32_e32 v3, 4, v3
	s_lshr_b32 s13, s12, 4
	s_and_b32 s14, s12, 15
	s_waitcnt lgkmcnt(0)
	s_mov_b64 s[16:17], s[8:9]
	s_movk_i32 s15, 0x2400
	s_sub_u32 s18, s13, 22
	s_cmp_lt_u32 s13, 40
	s_cbranch_scc1 .Ldc_sel
	s_mov_b64 s[16:17], s[10:11]
	s_movk_i32 s15, 0x1000
	s_sub_u32 s18, s13, 40
.Ldc_sel:
	s_lshl_b32 s19, s14, 6
	s_mul_i32 s19, s19, s15
	s_lshl_b32 s20, s18, 9
	s_add_u32 s19, s19, s20
	s_add_u32 s16, s16, s19
	s_addc_u32 s17, s17, 0
	s_lshl_b32 s20, s15, 3
	v_mul_lo_u32 v5, v4, s20
	v_add_u32_e32 v5, v5, v3
	global_load_dwordx4 v[8:11], v5, s[16:17]
	s_add_u32 s16, s16, s15
	s_addc_u32 s17, s17, 0
	global_load_dwordx4 v[12:15], v5, s[16:17]
	s_add_u32 s16, s16, s15
	s_addc_u32 s17, s17, 0
	global_load_dwordx4 v[16:19], v5, s[16:17]
	s_add_u32 s16, s16, s15
	s_addc_u32 s17, s17, 0
	global_load_dwordx4 v[20:23], v5, s[16:17]
	s_add_u32 s16, s16, s15
	s_addc_u32 s17, s17, 0
	global_load_dwordx4 v[24:27], v5, s[16:17]
	s_add_u32 s16, s16, s15
	s_addc_u32 s17, s17, 0
	global_load_dwordx4 v[28:31], v5, s[16:17]
	s_add_u32 s16, s16, s15
	s_addc_u32 s17, s17, 0
	global_load_dwordx4 v[32:35], v5, s[16:17]
	s_add_u32 s16, s16, s15
	s_addc_u32 s17, s17, 0
	global_load_dwordx4 v[36:39], v5, s[16:17]
	s_lshl_b32 s19, s12, 14
	s_add_u32 s20, s100, s19
	s_addc_u32 s21, s101, 0
	s_waitcnt vmcnt(0)
	v_cvt_pk_bf16_f32 v200, v8, v12
	v_cvt_pk_bf16_f32 v201, v16, v20
	v_cvt_pk_bf16_f32 v202, v24, v28
	v_cvt_pk_bf16_f32 v203, v32, v36
	global_store_dwordx4 v2, v[200:203], s[20:21]
	v_cvt_pk_bf16_f32 v204, v9, v13
	v_cvt_pk_bf16_f32 v205, v17, v21
	v_cvt_pk_bf16_f32 v206, v25, v29
	v_cvt_pk_bf16_f32 v207, v33, v37
	global_store_dwordx4 v2, v[204:207], s[20:21] offset:1024
	v_cvt_pk_bf16_f32 v208, v10, v14
	v_cvt_pk_bf16_f32 v209, v18, v22
	v_cvt_pk_bf16_f32 v210, v26, v30
	v_cvt_pk_bf16_f32 v211, v34, v38
	global_store_dwordx4 v2, v[208:211], s[20:21] offset:2048
	v_cvt_pk_bf16_f32 v212, v11, v15
	v_cvt_pk_bf16_f32 v213, v19, v23
	v_cvt_pk_bf16_f32 v214, v27, v31
	v_cvt_pk_bf16_f32 v215, v35, v39
	global_store_dwordx4 v2, v[212:215], s[20:21] offset:3072
